# phase_up Q and K epilogues: per-block LDS transpose, 16-byte row-major stores, one barrier at unit end
# speedup vs baseline: 1.0216x; 1.0216x over previous
.LBB0_915:
	s_or_b64 exec, exec, s[0:1]
	v_lshl_add_u64 v[0:1], s[26:27], 0, v[24:25]
	v_add_u32_e32 v24, v148, v121
	v_ashrrev_i32_e32 v25, 31, v24
	v_lshlrev_b64 v[22:23], v22, v[24:25]
	v_mov_b32_e32 v39, v4
	v_lshl_add_u64 v[22:23], v[22:23], 0, v[38:39]
	v_mad_u64_u32 v[0:1], s[0:1], v22, s50, v[0:1]
	v_mad_i32_i24 v1, v23, s50, v1
	v_lshl_add_u64 v[0:1], v[118:119], 1, v[0:1]
	v_mov_b32_e32 v3, v4
	v_lshl_add_u64 v[0:1], v[0:1], 0, v[2:3]
	v_pk_mul_f32 v[2:3], v[6:7], s[64:65] op_sel_hi:[1,0]
	v_pk_mul_f32 v[6:7], v[8:9], s[64:65] op_sel_hi:[1,0]
	v_cvt_pk_bf16_f32 v2, v2, v3
	v_cvt_pk_bf16_f32 v3, v6, v7
	s_nop 0
	v_readfirstlane_b32 s70, v0
	v_readfirstlane_b32 s71, v1
	ds_write_b64 v182, v[2:3]
	v_pk_mul_f32 v[2:3], v[10:11], s[64:65] op_sel_hi:[1,0]
	v_pk_mul_f32 v[6:7], v[12:13], s[64:65] op_sel_hi:[1,0]
	v_cvt_pk_bf16_f32 v2, v2, v3
	v_cvt_pk_bf16_f32 v3, v6, v7
	ds_write_b64 v182, v[2:3] offset:16
	v_pk_mul_f32 v[2:3], v[14:15], s[64:65] op_sel_hi:[1,0]
	v_pk_mul_f32 v[6:7], v[16:17], s[64:65] op_sel_hi:[1,0]
	v_cvt_pk_bf16_f32 v2, v2, v3
	v_cvt_pk_bf16_f32 v3, v6, v7
	ds_write_b64 v182, v[2:3] offset:32
	v_pk_mul_f32 v[2:3], v[18:19], s[64:65] op_sel_hi:[1,0]
	v_pk_mul_f32 v[6:7], v[20:21], s[64:65] op_sel_hi:[1,0]
	v_cvt_pk_bf16_f32 v2, v2, v3
	v_cvt_pk_bf16_f32 v3, v6, v7
	ds_write_b64 v182, v[2:3] offset:48
	ds_read_b128 v[186:189], v183
	ds_read_b128 v[190:193], v183 offset:1280
	s_waitcnt lgkmcnt(1)
	global_store_dwordx4 v184, v[186:189], s[70:71]
	s_waitcnt lgkmcnt(0)
	global_store_dwordx4 v184, v[190:193], s[70:71] offset:3072
.LBB0_916:
	s_barrier
	s_add_i32 s12, s12, s34
	s_cmpk_lt_i32 s12, 0x1d0
	s_cbranch_scc0 .LBB0_1000
.LBB0_917:
	v_mov_b32_e32 v139, v5
	s_movk_i32 s70, 0xa00
	s_movk_i32 s71, 0x50
	v_lshrrev_b32_e32 v186, 6, v5
	v_and_b32_e32 v187, 31, v5
	v_bfe_u32 v188, v5, 5, 1
	v_lshlrev_b32_e32 v188, 3, v188
	v_mad_u32_u24 v182, v186, s70, v188
	v_mad_u32_u24 v182, v187, s71, v182
	v_add_u32_e32 v182, 32, v182
	v_and_b32_e32 v187, 63, v5
	v_lshrrev_b32_e32 v188, 2, v187
	v_and_b32_e32 v187, 3, v187
	v_lshlrev_b32_e32 v187, 4, v187
	v_mad_u32_u24 v183, v186, s70, v187
	v_mad_u32_u24 v183, v188, s71, v183
	v_add_u32_e32 v183, 32, v183
	v_lshl_add_u32 v185, v188, 7, v187
	s_movk_i32 s70, 0xc0
	v_mad_u32_u24 v184, v188, s70, v187
	s_cmpk_gt_i32 s12, 0xbf
	s_mov_b64 s[0:1], -1
	s_cbranch_scc0 .LBB0_967
	s_add_i32 s0, s12, 0xffffff40
	v_ashrrev_i32_e32 v1, 6, v139
	v_bfe_u32 v0, v139, 3, 3
	s_lshr_b32 s68, s0, 2
	v_lshl_or_b32 v0, v1, 3, v0
	s_and_b32 s13, s12, 3
	s_lshl_b64 s[0:1], s[68:69], 16
	v_readlane_b32 s4, v254, 27
	v_lshlrev_b32_e32 v20, 10, v1
	v_lshrrev_b32_e32 v1, 1, v0
	v_readlane_b32 s5, v254, 28
	s_add_u32 s0, s4, s0
	v_xor_b32_e32 v6, v1, v139
	v_ashrrev_i32_e32 v1, 31, v0
	s_addc_u32 s1, s5, s1
	v_add_u32_e32 v21, 32, v20
	v_lshlrev_b64 v[0:1], 8, v[0:1]
	v_lshlrev_b32_e32 v6, 4, v6
	s_lshl_b32 s4, s13, 16
	v_lshl_add_u64 v[2:3], s[0:1], 0, v[0:1]
	v_and_b32_e32 v6, 0x70, v6
	v_mov_b32_e32 v7, v4
	v_readfirstlane_b32 s6, v21
	v_add_u32_e32 v10, 0x8000, v21
	s_add_u32 s4, s10, s4
	v_lshl_add_u64 v[2:3], v[2:3], 0, v[6:7]
	s_mov_b32 m0, s6
	v_readfirstlane_b32 s6, v10
	s_addc_u32 s5, s11, 0
	global_load_lds_dwordx4 v[2:3], off
	s_mov_b32 m0, s6
	s_mov_b64 s[6:7], 0x4000
	v_lshl_add_u64 v[8:9], s[4:5], 0, v[0:1]
	v_add_u32_e32 v14, 0x2000, v21
	v_lshl_add_u64 v[10:11], v[0:1], 0, s[6:7]
	v_lshl_add_u64 v[8:9], v[8:9], 0, v[6:7]
	v_lshl_add_u64 v[12:13], s[0:1], 0, v[10:11]
	v_readfirstlane_b32 s6, v14
	v_add_u32_e32 v14, 0xa000, v21
	global_load_lds_dwordx4 v[8:9], off
	v_lshl_add_u64 v[12:13], v[12:13], 0, v[6:7]
	s_mov_b32 m0, s6
	v_readfirstlane_b32 s6, v14
	global_load_lds_dwordx4 v[12:13], off
	s_mov_b32 m0, s6
	s_mov_b64 s[6:7], 0x8000
	v_lshl_add_u64 v[10:11], s[4:5], 0, v[10:11]
	v_add_u32_e32 v18, 0x4000, v21
	v_lshl_add_u64 v[14:15], v[0:1], 0, s[6:7]
	v_lshl_add_u64 v[10:11], v[10:11], 0, v[6:7]
	v_lshl_add_u64 v[16:17], s[0:1], 0, v[14:15]
	v_readfirstlane_b32 s6, v18
	v_add_u32_e32 v18, 0xc000, v21
	global_load_lds_dwordx4 v[10:11], off
	v_lshl_add_u64 v[16:17], v[16:17], 0, v[6:7]
	s_mov_b32 m0, s6
	v_readfirstlane_b32 s6, v18
	global_load_lds_dwordx4 v[16:17], off
	s_mov_b32 m0, s6
	s_mov_b64 s[6:7], 0xc000
	v_lshl_add_u64 v[0:1], v[0:1], 0, s[6:7]
	v_lshl_add_u64 v[14:15], s[4:5], 0, v[14:15]
	v_add_u32_e32 v22, 0x6000, v21
	v_lshl_add_u64 v[18:19], s[0:1], 0, v[0:1]
	v_lshl_add_u64 v[0:1], s[4:5], 0, v[0:1]
	v_lshl_add_u64 v[14:15], v[14:15], 0, v[6:7]
	v_lshl_add_u64 v[18:19], v[18:19], 0, v[6:7]
	v_readfirstlane_b32 s0, v22
	v_lshl_add_u64 v[0:1], v[0:1], 0, v[6:7]
	v_add_u32_e32 v6, 0xe000, v21
	global_load_lds_dwordx4 v[14:15], off
	s_mov_b32 m0, s0
	v_readfirstlane_b32 s0, v6
	v_lshrrev_b32_e32 v6, 5, v139
	v_bfe_u32 v148, v139, 1, 3
	v_bitop3_b32 v6, v6, v148, 1 bitop3:0x6c
	global_load_lds_dwordx4 v[18:19], off
	s_mov_b32 m0, s0
	v_lshlrev_b32_e32 v149, 4, v6
	v_lshlrev_b32_e32 v6, 7, v139
	s_add_i32 s0, 32, 0x10000
	v_and_b32_e32 v150, 0x6f80, v6
	v_add_u32_e32 v6, s0, v20
	global_load_lds_dwordx4 v[0:1], off
	v_readfirstlane_b32 s1, v6
	v_lshl_add_u64 v[2:3], v[2:3], 0, s[54:55]
	s_mov_b32 m0, s1
	s_waitcnt vmcnt(0)
	s_waitcnt vmcnt(0) lgkmcnt(0)
	s_barrier
	global_load_lds_dwordx4 v[2:3], off
	v_lshl_add_u64 v[2:3], v[8:9], 0, s[54:55]
	v_add_u32_e32 v8, 0x8000, v6
	v_and_b32_e32 v152, 31, v139
	v_readfirstlane_b32 s1, v8
	v_add_u32_e32 v8, 0x2000, v6
	s_mov_b32 m0, s1
	v_readfirstlane_b32 s1, v8
	v_add_u32_e32 v8, 0xa000, v6
	global_load_lds_dwordx4 v[2:3], off
	v_lshl_add_u64 v[2:3], v[12:13], 0, s[54:55]
	s_mov_b32 m0, s1
	v_readfirstlane_b32 s1, v8
	v_add_u32_e32 v8, 0x4000, v6
	global_load_lds_dwordx4 v[2:3], off
	v_lshl_add_u64 v[2:3], v[10:11], 0, s[54:55]
	s_mov_b32 m0, s1
	v_readfirstlane_b32 s1, v8
	v_add_u32_e32 v8, 0xc000, v6
	global_load_lds_dwordx4 v[2:3], off
	v_lshl_add_u64 v[2:3], v[16:17], 0, s[54:55]
	s_mov_b32 m0, s1
	v_readfirstlane_b32 s1, v8
	v_add_u32_e32 v8, 0x6000, v6
	global_load_lds_dwordx4 v[2:3], off
	v_lshl_add_u64 v[2:3], v[14:15], 0, s[54:55]
	s_mov_b32 m0, s1
	v_readfirstlane_b32 s1, v8
	global_load_lds_dwordx4 v[2:3], off
	v_lshl_add_u64 v[2:3], v[18:19], 0, s[54:55]
	s_mov_b32 m0, s1
	v_lshrrev_b32_e32 v7, 1, v139
	global_load_lds_dwordx4 v[2:3], off
	v_add_u32_e32 v2, 0xe000, v6
	v_lshl_add_u64 v[0:1], v[0:1], 0, s[54:55]
	v_readfirstlane_b32 s1, v2
	s_mov_b32 m0, s1
	s_mov_b32 s1, 0x1ffff80
	v_and_or_b32 v7, v7, s1, v152
	v_add_u32_e32 v6, 32, v149
	v_lshlrev_b32_e32 v151, 7, v7
	global_load_lds_dwordx4 v[0:1], off
	v_add_u32_e32 v10, v6, v150
	v_add_u32_e32 v14, v6, v151
	ds_read_b128 v[0:3], v10 offset:32768
	ds_read_b128 v[6:9], v14
	ds_read_b128 v[10:13], v10 offset:36864
	s_waitcnt lgkmcnt(0)
	v_mfma_f32_32x32x16_bf16 v[118:133], v[0:3], v[6:9], 0
	v_bfe_u32 v153, v139, 5, 1
	s_add_i32 s1, 32, 0x18000
	v_mfma_f32_32x32x16_bf16 v[102:117], v[10:13], v[6:9], 0
	ds_read_b128 v[6:9], v14 offset:4096
	s_waitcnt lgkmcnt(0)
	v_mfma_f32_32x32x16_bf16 v[86:101], v[0:3], v[6:9], 0
	v_mfma_f32_32x32x16_bf16 v[70:85], v[10:13], v[6:9], 0
	ds_read_b128 v[6:9], v14 offset:8192
	s_waitcnt lgkmcnt(0)
	v_mfma_f32_32x32x16_bf16 v[54:69], v[0:3], v[6:9], 0
	v_mfma_f32_32x32x16_bf16 v[38:53], v[10:13], v[6:9], 0
	ds_read_b128 v[6:9], v14 offset:12288
	s_waitcnt lgkmcnt(0)
	v_mfma_f32_32x32x16_bf16 v[22:37], v[0:3], v[6:9], 0
	v_bitop3_b32 v0, v153, v148, 2 bitop3:0x36
	v_lshlrev_b32_e32 v154, 4, v0
	v_add_u32_e32 v134, 32, v154
	v_add_u32_e32 v144, v134, v150
	v_add_u32_e32 v155, v134, v151
	ds_read_b128 v[0:3], v144 offset:32768
	ds_read_b128 v[134:137], v155
	ds_read_b128 v[144:147], v144 offset:36864
	s_waitcnt lgkmcnt(0)
	v_mfma_f32_32x32x16_bf16 v[118:133], v[0:3], v[134:137], v[118:133]
	v_mfma_f32_32x32x16_bf16 v[102:117], v[144:147], v[134:137], v[102:117]
	ds_read_b128 v[134:137], v155 offset:4096
	s_waitcnt lgkmcnt(0)
	v_mfma_f32_32x32x16_bf16 v[86:101], v[0:3], v[134:137], v[86:101]
	v_mfma_f32_32x32x16_bf16 v[70:85], v[144:147], v[134:137], v[70:85]
	ds_read_b128 v[134:137], v155 offset:8192
	v_mfma_f32_32x32x16_bf16 v[6:21], v[10:13], v[6:9], 0
	s_waitcnt lgkmcnt(0)
	v_mfma_f32_32x32x16_bf16 v[54:69], v[0:3], v[134:137], v[54:69]
	v_mfma_f32_32x32x16_bf16 v[38:53], v[144:147], v[134:137], v[38:53]
	ds_read_b128 v[134:137], v155 offset:12288
	s_waitcnt lgkmcnt(0)
	v_mfma_f32_32x32x16_bf16 v[22:37], v[0:3], v[134:137], v[22:37]
	v_bitop3_b32 v0, v153, v148, 4 bitop3:0x36
	v_lshlrev_b32_e32 v155, 4, v0
	v_mfma_f32_32x32x16_bf16 v[6:21], v[144:147], v[134:137], v[6:21]
	v_add_u32_e32 v134, 32, v155
	v_add_u32_e32 v144, v134, v150
	v_add_u32_e32 v156, v134, v151
	ds_read_b128 v[0:3], v144 offset:32768
	ds_read_b128 v[134:137], v156
	ds_read_b128 v[144:147], v144 offset:36864
	s_waitcnt lgkmcnt(0)
	v_mfma_f32_32x32x16_bf16 v[118:133], v[0:3], v[134:137], v[118:133]
	v_mfma_f32_32x32x16_bf16 v[102:117], v[144:147], v[134:137], v[102:117]
	ds_read_b128 v[134:137], v156 offset:4096
	s_waitcnt lgkmcnt(0)
	v_mfma_f32_32x32x16_bf16 v[86:101], v[0:3], v[134:137], v[86:101]
	v_mfma_f32_32x32x16_bf16 v[70:85], v[144:147], v[134:137], v[70:85]
	ds_read_b128 v[134:137], v156 offset:8192
	s_waitcnt lgkmcnt(0)
	v_mfma_f32_32x32x16_bf16 v[54:69], v[0:3], v[134:137], v[54:69]
	v_mfma_f32_32x32x16_bf16 v[38:53], v[144:147], v[134:137], v[38:53]
	ds_read_b128 v[134:137], v156 offset:12288
	s_waitcnt lgkmcnt(0)
	v_mfma_f32_32x32x16_bf16 v[22:37], v[0:3], v[134:137], v[22:37]
	v_bitop3_b32 v0, v153, v148, 6 bitop3:0x36
	v_lshlrev_b32_e32 v148, 4, v0
	v_mfma_f32_32x32x16_bf16 v[6:21], v[144:147], v[134:137], v[6:21]
	v_add_u32_e32 v134, 32, v148
	v_add_u32_e32 v144, v134, v150
	v_add_u32_e32 v153, v134, v151
	ds_read_b128 v[0:3], v144 offset:32768
	ds_read_b128 v[134:137], v153
	ds_read_b128 v[144:147], v144 offset:36864
	s_waitcnt lgkmcnt(0)
	v_mfma_f32_32x32x16_bf16 v[118:133], v[0:3], v[134:137], v[118:133]
	v_mfma_f32_32x32x16_bf16 v[102:117], v[144:147], v[134:137], v[102:117]
	ds_read_b128 v[134:137], v153 offset:4096
	s_waitcnt lgkmcnt(0)
	v_mfma_f32_32x32x16_bf16 v[86:101], v[0:3], v[134:137], v[86:101]
	v_mfma_f32_32x32x16_bf16 v[70:85], v[144:147], v[134:137], v[70:85]
	ds_read_b128 v[134:137], v153 offset:8192
	s_waitcnt lgkmcnt(0)
	v_mfma_f32_32x32x16_bf16 v[54:69], v[0:3], v[134:137], v[54:69]
	v_mfma_f32_32x32x16_bf16 v[38:53], v[144:147], v[134:137], v[38:53]
	ds_read_b128 v[134:137], v153 offset:12288
	s_waitcnt vmcnt(0)
	s_waitcnt vmcnt(0) lgkmcnt(0)
	s_barrier
	v_mfma_f32_32x32x16_bf16 v[6:21], v[144:147], v[134:137], v[6:21]
	v_add3_u32 v144, s1, v149, v150
	v_add3_u32 v149, s0, v149, v151
	v_mfma_f32_32x32x16_bf16 v[22:37], v[0:3], v[134:137], v[22:37]
	ds_read_b128 v[0:3], v144
	ds_read_b128 v[134:137], v149
	ds_read_b128 v[144:147], v144 offset:4096
	s_waitcnt lgkmcnt(1)
	v_mfma_f32_32x32x16_bf16 v[118:133], v[0:3], v[134:137], v[118:133]
	s_waitcnt lgkmcnt(0)
	v_mfma_f32_32x32x16_bf16 v[102:117], v[144:147], v[134:137], v[102:117]
	ds_read_b128 v[134:137], v149 offset:4096
	s_waitcnt lgkmcnt(0)
	v_mfma_f32_32x32x16_bf16 v[86:101], v[0:3], v[134:137], v[86:101]
	v_mfma_f32_32x32x16_bf16 v[70:85], v[144:147], v[134:137], v[70:85]
	ds_read_b128 v[134:137], v149 offset:8192
	s_waitcnt lgkmcnt(0)
	v_mfma_f32_32x32x16_bf16 v[54:69], v[0:3], v[134:137], v[54:69]
	v_mfma_f32_32x32x16_bf16 v[38:53], v[144:147], v[134:137], v[38:53]
	ds_read_b128 v[134:137], v149 offset:12288
	v_add3_u32 v149, s0, v154, v151
	s_waitcnt lgkmcnt(0)
	v_mfma_f32_32x32x16_bf16 v[6:21], v[144:147], v[134:137], v[6:21]
	v_add3_u32 v144, s1, v154, v150
	v_mfma_f32_32x32x16_bf16 v[22:37], v[0:3], v[134:137], v[22:37]
	ds_read_b128 v[0:3], v144
	ds_read_b128 v[134:137], v149
	ds_read_b128 v[144:147], v144 offset:4096
	s_waitcnt lgkmcnt(1)
	v_mfma_f32_32x32x16_bf16 v[118:133], v[0:3], v[134:137], v[118:133]
	s_waitcnt lgkmcnt(0)
	v_mfma_f32_32x32x16_bf16 v[102:117], v[144:147], v[134:137], v[102:117]
	ds_read_b128 v[134:137], v149 offset:4096
	s_waitcnt lgkmcnt(0)
	v_mfma_f32_32x32x16_bf16 v[86:101], v[0:3], v[134:137], v[86:101]
	v_mfma_f32_32x32x16_bf16 v[70:85], v[144:147], v[134:137], v[70:85]
	ds_read_b128 v[134:137], v149 offset:8192
	s_waitcnt lgkmcnt(0)
	v_mfma_f32_32x32x16_bf16 v[54:69], v[0:3], v[134:137], v[54:69]
	v_mfma_f32_32x32x16_bf16 v[38:53], v[144:147], v[134:137], v[38:53]
	ds_read_b128 v[134:137], v149 offset:12288
	v_add3_u32 v149, s0, v155, v151
	s_waitcnt lgkmcnt(0)
	v_mfma_f32_32x32x16_bf16 v[6:21], v[144:147], v[134:137], v[6:21]
	v_add3_u32 v144, s1, v155, v150
	v_mfma_f32_32x32x16_bf16 v[22:37], v[0:3], v[134:137], v[22:37]
	ds_read_b128 v[0:3], v144
	ds_read_b128 v[134:137], v149
	ds_read_b128 v[144:147], v144 offset:4096
	s_waitcnt lgkmcnt(1)
	v_mfma_f32_32x32x16_bf16 v[118:133], v[0:3], v[134:137], v[118:133]
	s_waitcnt lgkmcnt(0)
	v_mfma_f32_32x32x16_bf16 v[102:117], v[144:147], v[134:137], v[102:117]
	ds_read_b128 v[134:137], v149 offset:4096
	s_waitcnt lgkmcnt(0)
	v_mfma_f32_32x32x16_bf16 v[86:101], v[0:3], v[134:137], v[86:101]
	v_mfma_f32_32x32x16_bf16 v[70:85], v[144:147], v[134:137], v[70:85]
	ds_read_b128 v[134:137], v149 offset:8192
	s_waitcnt lgkmcnt(0)
	v_mfma_f32_32x32x16_bf16 v[54:69], v[0:3], v[134:137], v[54:69]
	v_mfma_f32_32x32x16_bf16 v[38:53], v[144:147], v[134:137], v[38:53]
	ds_read_b128 v[134:137], v149 offset:12288
	s_waitcnt lgkmcnt(0)
	v_mfma_f32_32x32x16_bf16 v[6:21], v[144:147], v[134:137], v[6:21]
	v_add3_u32 v144, s1, v148, v150
	ds_read_b128 v[154:157], v144 offset:4096
	v_add3_u32 v145, s0, v148, v151
	s_movk_i32 s0, 0x9f
	v_mfma_f32_32x32x16_bf16 v[22:37], v[0:3], v[134:137], v[22:37]
	ds_read_b128 v[0:3], v144
	ds_read_b128 v[134:137], v145
	s_waitcnt lgkmcnt(0)
	v_mfma_f32_32x32x16_bf16 v[118:133], v[0:3], v[134:137], v[118:133]
	v_mfma_f32_32x32x16_bf16 v[102:117], v[154:157], v[134:137], v[102:117]
	ds_read_b128 v[134:137], v145 offset:4096
	ds_read_b128 v[148:151], v145 offset:8192
	ds_read_b128 v[158:161], v145 offset:12288
	s_waitcnt vmcnt(0)
	s_waitcnt lgkmcnt(0)
	s_barrier
	v_mfma_f32_32x32x16_bf16 v[86:101], v[0:3], v[134:137], v[86:101]
	v_mfma_f32_32x32x16_bf16 v[70:85], v[154:157], v[134:137], v[70:85]
	v_ashrrev_i32_e32 v134, 1, v139
	v_and_b32_e32 v134, 0xffffff80, v134
	v_or_b32_e32 v135, v134, v152
	v_lshl_add_u32 v144, s68, 8, v135
	v_bitop3_b32 v146, v134, s0, v152 bitop3:0xc8
	v_subrev_co_u32_e32 v134, vcc, 0x4000, v144
	v_mfma_f32_32x32x16_bf16 v[54:69], v[0:3], v[148:151], v[54:69]
	v_lshrrev_b32_e32 v137, 9, v134
	v_and_b32_e32 v134, 0x19f, v144
	v_ashrrev_i32_e32 v136, 8, v144
	s_mov_b64 s[4:5], vcc
	v_cmp_lt_i32_e64 s[6:7], s89, v144
	v_mov_b32_e32 v152, v146
	v_mov_b32_e32 v145, v136
	v_mfma_f32_32x32x16_bf16 v[38:53], v[154:157], v[148:151], v[38:53]
	v_or_b32_e32 v149, 0x1000, v134
	v_add_u32_e32 v134, 0xffffe000, v144
	v_lshrrev_b32_e32 v150, 12, v134
	v_and_b32_e32 v151, 0xf9f, v144
	v_mov_b64_e32 v[134:135], 0xc952000
	v_cndmask_b32_e64 v147, v149, v151, s[4:5]
	v_cndmask_b32_e64 v148, v137, v150, s[4:5]
	v_mfma_f32_32x32x16_bf16 v[22:37], v[0:3], v[158:161], v[22:37]
	v_mov_b64_e32 v[2:3], 0x100
	v_mov_b64_e32 v[0:1], 0xdb62000
	v_mfma_f32_32x32x16_bf16 v[6:21], v[154:157], v[158:161], v[6:21]
	s_and_saveexec_b64 s[0:1], s[6:7]
	v_cndmask_b32_e64 v152, v149, v151, s[4:5]
	v_cndmask_b32_e64 v145, v137, v150, s[4:5]
	v_mov_b64_e32 v[2:3], 0x1200
	v_mov_b64_e32 v[134:135], 0xd152000
	v_mov_b64_e32 v[0:1], 0xe362000
	s_or_b64 exec, exec, s[0:1]
	v_lshrrev_b32_e32 v3, 3, v139
	v_and_b32_e32 v137, 0x80, v139
	v_lshl_or_b32 v137, s13, 8, v137
	v_and_b32_e32 v151, 4, v3
	v_or_b32_e32 v149, 0xffffffc0, v151
	v_lshrrev_b32_e32 v137, 7, v137
	v_and_b32_e32 v150, 64, v139
	v_lshl_or_b32 v3, v145, 3, v137
	v_cmp_ne_u32_e32 vcc, 0, v150
	v_add_u32_e32 v145, v149, v150
	s_and_saveexec_b64 s[0:1], vcc
	s_xor_b64 s[0:1], exec, s[0:1]
	s_cbranch_execz .LBB0_922
	v_mad_i64_i32 v[134:135], s[14:15], v2, v3, 0
	v_lshl_add_u64 v[0:1], s[26:27], 0, v[0:1]
	v_lshlrev_b64 v[134:135], 7, v[134:135]
	v_lshl_add_u64 v[0:1], v[0:1], 0, v[134:135]
	v_mad_u64_u32 v[134:135], s[14:15], v2, v145, 0
	v_lshl_add_u64 v[0:1], v[134:135], 1, v[0:1]
	v_lshlrev_b32_e32 v134, 1, v152
	v_mov_b32_e32 v135, v4
	v_lshl_add_u64 v[0:1], v[0:1], 0, v[134:135]
	v_cvt_pk_bf16_f32 v3, v118, s0
	global_store_short v[0:1], v3, off
	v_cvt_pk_bf16_f32 v3, v119, s0
	v_lshlrev_b32_e32 v118, 1, v2
	v_mov_b32_e32 v119, v4
	v_lshl_add_u64 v[0:1], v[0:1], 0, v[118:119]
	global_store_short v[0:1], v3, off
	v_cvt_pk_bf16_f32 v3, v120, s0
	v_lshl_add_u64 v[0:1], v[0:1], 0, v[118:119]
	global_store_short v[0:1], v3, off
	v_cvt_pk_bf16_f32 v3, v121, s0
	v_lshl_add_u64 v[0:1], v[0:1], 0, v[118:119]
	global_store_short v[0:1], v3, off
	v_cvt_pk_bf16_f32 v3, v122, s0
	v_mad_u64_u32 v[0:1], s[14:15], v2, 10, v[0:1]
	global_store_short v[0:1], v3, off
	v_cvt_pk_bf16_f32 v3, v123, s0
	v_lshl_add_u64 v[0:1], v[0:1], 0, v[118:119]
	global_store_short v[0:1], v3, off
	v_cvt_pk_bf16_f32 v3, v124, s0
	v_lshl_add_u64 v[0:1], v[0:1], 0, v[118:119]
	global_store_short v[0:1], v3, off
	v_cvt_pk_bf16_f32 v3, v125, s0
	v_lshl_add_u64 v[0:1], v[0:1], 0, v[118:119]
	global_store_short v[0:1], v3, off
	v_cvt_pk_bf16_f32 v3, v126, s0
	v_mad_u64_u32 v[0:1], s[14:15], v2, 10, v[0:1]
	global_store_short v[0:1], v3, off
	v_cvt_pk_bf16_f32 v3, v127, s0
	v_lshl_add_u64 v[0:1], v[0:1], 0, v[118:119]
	global_store_short v[0:1], v3, off
	v_cvt_pk_bf16_f32 v3, v128, s0
	v_lshl_add_u64 v[0:1], v[0:1], 0, v[118:119]
	global_store_short v[0:1], v3, off
	v_cvt_pk_bf16_f32 v3, v129, s0
	v_lshl_add_u64 v[0:1], v[0:1], 0, v[118:119]
	global_store_short v[0:1], v3, off
	v_cvt_pk_bf16_f32 v3, v130, s0
	v_mad_u64_u32 v[0:1], s[14:15], v2, 10, v[0:1]
	global_store_short v[0:1], v3, off
	v_cvt_pk_bf16_f32 v2, v131, s0
	v_lshl_add_u64 v[0:1], v[0:1], 0, v[118:119]
	global_store_short v[0:1], v2, off
	v_cvt_pk_bf16_f32 v2, v132, s0
	v_lshl_add_u64 v[0:1], v[0:1], 0, v[118:119]
	global_store_short v[0:1], v2, off
	v_cvt_pk_bf16_f32 v2, v133, s0
	v_lshl_add_u64 v[0:1], v[0:1], 0, v[118:119]
	global_store_short v[0:1], v2, off
.LBB0_922:
	s_or_saveexec_b64 s[0:1], s[0:1]
	v_lshlrev_b32_e32 v0, 1, v151
	s_xor_b64 exec, exec, s[0:1]
	s_cbranch_execz .LBB0_924
	v_lshl_add_u64 v[134:135], s[26:27], 0, v[134:135]
	v_lshlrev_b32_e32 v1, 7, v2
	v_mad_i64_i32 v[2:3], s[14:15], v1, v3, v[134:135]
	v_lshlrev_b32_e32 v134, 7, v152
	v_mov_b32_e32 v135, v4
	v_lshl_add_u64 v[2:3], v[2:3], 0, v[134:135]
	v_mov_b32_e32 v1, v4
	v_lshl_add_u64 v[2:3], v[2:3], 0, v[0:1]
	v_cvt_pk_bf16_f32 v118, v118, v119
	v_cvt_pk_bf16_f32 v119, v120, v121
	s_nop 0
	v_readfirstlane_b32 s70, v2
	v_readfirstlane_b32 s71, v3
	ds_write_b64 v182, v[118:119]
	v_cvt_pk_bf16_f32 v118, v122, v123
	v_cvt_pk_bf16_f32 v119, v124, v125
	ds_write_b64 v182, v[118:119] offset:16
	v_cvt_pk_bf16_f32 v118, v126, v127
	v_cvt_pk_bf16_f32 v119, v128, v129
	ds_write_b64 v182, v[118:119] offset:32
	v_cvt_pk_bf16_f32 v118, v130, v131
	v_cvt_pk_bf16_f32 v119, v132, v133
	ds_write_b64 v182, v[118:119] offset:48
	ds_read_b128 v[186:189], v183
	ds_read_b128 v[190:193], v183 offset:1280
	s_waitcnt lgkmcnt(1)
	global_store_dwordx4 v185, v[186:189], s[70:71]
	s_waitcnt lgkmcnt(0)
	global_store_dwordx4 v185, v[190:193], s[70:71] offset:2048

.LBB0_928:
	s_andn2_saveexec_b64 s[0:1], s[0:1]
	s_cbranch_execz .LBB0_930
	v_lshl_add_u64 v[118:119], s[26:27], 0, v[118:119]
	v_lshlrev_b32_e32 v2, 7, v2
	v_mad_i64_i32 v[2:3], s[6:7], v2, v1, v[118:119]
	v_lshlrev_b32_e32 v118, 7, v146
	v_mov_b32_e32 v119, v4
	v_lshl_add_u64 v[2:3], v[2:3], 0, v[118:119]
	v_mov_b32_e32 v1, v4
	v_lshl_add_u64 v[2:3], v[2:3], 0, v[0:1]
	v_cvt_pk_bf16_f32 v102, v102, v103
	v_cvt_pk_bf16_f32 v103, v104, v105
	s_nop 0
	v_readfirstlane_b32 s70, v2
	v_readfirstlane_b32 s71, v3
	ds_write_b64 v182, v[102:103]
	v_cvt_pk_bf16_f32 v102, v106, v107
	v_cvt_pk_bf16_f32 v103, v108, v109
	ds_write_b64 v182, v[102:103] offset:16
	v_cvt_pk_bf16_f32 v102, v110, v111
	v_cvt_pk_bf16_f32 v103, v112, v113
	ds_write_b64 v182, v[102:103] offset:32
	v_cvt_pk_bf16_f32 v102, v114, v115
	v_cvt_pk_bf16_f32 v103, v116, v117
	ds_write_b64 v182, v[102:103] offset:48
	ds_read_b128 v[186:189], v183
	ds_read_b128 v[190:193], v183 offset:1280
	s_waitcnt lgkmcnt(1)
	global_store_dwordx4 v185, v[186:189], s[70:71] offset:64
	s_waitcnt lgkmcnt(0)
	global_store_dwordx4 v185, v[190:193], s[70:71] offset:2112

.LBB0_934:
	s_andn2_saveexec_b64 s[6:7], s[6:7]
	s_cbranch_execz .LBB0_936
	v_lshl_add_u64 v[102:103], s[26:27], 0, v[102:103]
	v_lshlrev_b32_e32 v2, 7, v2
	v_mad_i64_i32 v[2:3], s[14:15], v2, v3, v[102:103]
	v_lshlrev_b32_e32 v102, 7, v1
	v_mov_b32_e32 v103, v4
	v_lshl_add_u64 v[2:3], v[2:3], 0, v[102:103]
	v_mov_b32_e32 v1, v4
	v_lshl_add_u64 v[2:3], v[2:3], 0, v[0:1]
	v_cvt_pk_bf16_f32 v86, v86, v87
	v_cvt_pk_bf16_f32 v87, v88, v89
	s_nop 0
	v_readfirstlane_b32 s70, v2
	v_readfirstlane_b32 s71, v3
	ds_write_b64 v182, v[86:87]
	v_cvt_pk_bf16_f32 v86, v90, v91
	v_cvt_pk_bf16_f32 v87, v92, v93
	ds_write_b64 v182, v[86:87] offset:16
	v_cvt_pk_bf16_f32 v86, v94, v95
	v_cvt_pk_bf16_f32 v87, v96, v97
	ds_write_b64 v182, v[86:87] offset:32
	v_cvt_pk_bf16_f32 v86, v98, v99
	v_cvt_pk_bf16_f32 v87, v100, v101
	ds_write_b64 v182, v[86:87] offset:48
	ds_read_b128 v[186:189], v183
	ds_read_b128 v[190:193], v183 offset:1280
	s_waitcnt lgkmcnt(1)
	global_store_dwordx4 v185, v[186:189], s[70:71]
	s_waitcnt lgkmcnt(0)
	global_store_dwordx4 v185, v[190:193], s[70:71] offset:2048

.LBB0_940:
	s_andn2_saveexec_b64 s[0:1], s[0:1]
	s_cbranch_execz .LBB0_942
	v_lshl_add_u64 v[86:87], s[26:27], 0, v[86:87]
	v_lshlrev_b32_e32 v2, 7, v2
	v_mad_i64_i32 v[2:3], s[6:7], v2, v1, v[86:87]
	v_lshlrev_b32_e32 v86, 7, v106
	v_mov_b32_e32 v87, v4
	v_lshl_add_u64 v[2:3], v[2:3], 0, v[86:87]
	v_mov_b32_e32 v1, v4
	v_lshl_add_u64 v[2:3], v[2:3], 0, v[0:1]
	v_cvt_pk_bf16_f32 v70, v70, v71
	v_cvt_pk_bf16_f32 v71, v72, v73
	s_nop 0
	v_readfirstlane_b32 s70, v2
	v_readfirstlane_b32 s71, v3
	ds_write_b64 v182, v[70:71]
	v_cvt_pk_bf16_f32 v70, v74, v75
	v_cvt_pk_bf16_f32 v71, v76, v77
	ds_write_b64 v182, v[70:71] offset:16
	v_cvt_pk_bf16_f32 v70, v78, v79
	v_cvt_pk_bf16_f32 v71, v80, v81
	ds_write_b64 v182, v[70:71] offset:32
	v_cvt_pk_bf16_f32 v70, v82, v83
	v_cvt_pk_bf16_f32 v71, v84, v85
	ds_write_b64 v182, v[70:71] offset:48
	ds_read_b128 v[186:189], v183
	ds_read_b128 v[190:193], v183 offset:1280
	s_waitcnt lgkmcnt(1)
	global_store_dwordx4 v185, v[186:189], s[70:71] offset:64
	s_waitcnt lgkmcnt(0)
	global_store_dwordx4 v185, v[190:193], s[70:71] offset:2112

.LBB0_946:
	s_andn2_saveexec_b64 s[6:7], s[6:7]
	s_cbranch_execz .LBB0_948
	v_lshl_add_u64 v[70:71], s[26:27], 0, v[70:71]
	v_lshlrev_b32_e32 v2, 7, v2
	v_mad_i64_i32 v[2:3], s[14:15], v2, v3, v[70:71]
	v_lshlrev_b32_e32 v70, 7, v1
	v_mov_b32_e32 v71, v4
	v_lshl_add_u64 v[2:3], v[2:3], 0, v[70:71]
	v_mov_b32_e32 v1, v4
	v_lshl_add_u64 v[2:3], v[2:3], 0, v[0:1]
	v_cvt_pk_bf16_f32 v54, v54, v55
	v_cvt_pk_bf16_f32 v55, v56, v57
	s_nop 0
	v_readfirstlane_b32 s70, v2
	v_readfirstlane_b32 s71, v3
	ds_write_b64 v182, v[54:55]
	v_cvt_pk_bf16_f32 v54, v58, v59
	v_cvt_pk_bf16_f32 v55, v60, v61
	ds_write_b64 v182, v[54:55] offset:16
	v_cvt_pk_bf16_f32 v54, v62, v63
	v_cvt_pk_bf16_f32 v55, v64, v65
	ds_write_b64 v182, v[54:55] offset:32
	v_cvt_pk_bf16_f32 v54, v66, v67
	v_cvt_pk_bf16_f32 v55, v68, v69
	ds_write_b64 v182, v[54:55] offset:48
	ds_read_b128 v[186:189], v183
	ds_read_b128 v[190:193], v183 offset:1280
	s_waitcnt lgkmcnt(1)
	global_store_dwordx4 v185, v[186:189], s[70:71]
	s_waitcnt lgkmcnt(0)
	global_store_dwordx4 v185, v[190:193], s[70:71] offset:2048

.LBB0_952:
	s_andn2_saveexec_b64 s[0:1], s[0:1]
	s_cbranch_execz .LBB0_954
	v_lshl_add_u64 v[54:55], s[26:27], 0, v[54:55]
	v_lshlrev_b32_e32 v2, 7, v2
	v_mad_i64_i32 v[2:3], s[6:7], v2, v1, v[54:55]
	v_lshlrev_b32_e32 v54, 7, v74
	v_mov_b32_e32 v55, v4
	v_lshl_add_u64 v[2:3], v[2:3], 0, v[54:55]
	v_mov_b32_e32 v1, v4
	v_lshl_add_u64 v[2:3], v[2:3], 0, v[0:1]
	v_cvt_pk_bf16_f32 v38, v38, v39
	v_cvt_pk_bf16_f32 v39, v40, v41
	s_nop 0
	v_readfirstlane_b32 s70, v2
	v_readfirstlane_b32 s71, v3
	ds_write_b64 v182, v[38:39]
	v_cvt_pk_bf16_f32 v38, v42, v43
	v_cvt_pk_bf16_f32 v39, v44, v45
	ds_write_b64 v182, v[38:39] offset:16
	v_cvt_pk_bf16_f32 v38, v46, v47
	v_cvt_pk_bf16_f32 v39, v48, v49
	ds_write_b64 v182, v[38:39] offset:32
	v_cvt_pk_bf16_f32 v38, v50, v51
	v_cvt_pk_bf16_f32 v39, v52, v53
	ds_write_b64 v182, v[38:39] offset:48
	ds_read_b128 v[186:189], v183
	ds_read_b128 v[190:193], v183 offset:1280
	s_waitcnt lgkmcnt(1)
	global_store_dwordx4 v185, v[186:189], s[70:71] offset:64
	s_waitcnt lgkmcnt(0)
	global_store_dwordx4 v185, v[190:193], s[70:71] offset:2112

.LBB0_958:
	s_andn2_saveexec_b64 s[4:5], s[4:5]
	s_cbranch_execz .LBB0_960
	v_lshl_add_u64 v[38:39], s[26:27], 0, v[38:39]
	v_lshlrev_b32_e32 v2, 7, v2
	v_mad_i64_i32 v[2:3], s[6:7], v2, v3, v[38:39]
	v_lshlrev_b32_e32 v38, 7, v1
	v_mov_b32_e32 v39, v4
	v_lshl_add_u64 v[2:3], v[2:3], 0, v[38:39]
	v_mov_b32_e32 v1, v4
	v_lshl_add_u64 v[2:3], v[2:3], 0, v[0:1]
	v_cvt_pk_bf16_f32 v22, v22, v23
	v_cvt_pk_bf16_f32 v23, v24, v25
	s_nop 0
	v_readfirstlane_b32 s70, v2
	v_readfirstlane_b32 s71, v3
	ds_write_b64 v182, v[22:23]
	v_cvt_pk_bf16_f32 v22, v26, v27
	v_cvt_pk_bf16_f32 v23, v28, v29
	ds_write_b64 v182, v[22:23] offset:16
	v_cvt_pk_bf16_f32 v22, v30, v31
	v_cvt_pk_bf16_f32 v23, v32, v33
	ds_write_b64 v182, v[22:23] offset:32
	v_cvt_pk_bf16_f32 v22, v34, v35
	v_cvt_pk_bf16_f32 v23, v36, v37
	ds_write_b64 v182, v[22:23] offset:48
	ds_read_b128 v[186:189], v183
	ds_read_b128 v[190:193], v183 offset:1280
	s_waitcnt lgkmcnt(1)
	global_store_dwordx4 v185, v[186:189], s[70:71]
	s_waitcnt lgkmcnt(0)
	global_store_dwordx4 v185, v[190:193], s[70:71] offset:2048

.LBB0_964:
	s_andn2_saveexec_b64 s[0:1], s[0:1]
	s_cbranch_execz .LBB0_966
	v_lshl_add_u64 v[22:23], s[26:27], 0, v[22:23]
	v_lshlrev_b32_e32 v2, 7, v2
	v_mad_i64_i32 v[2:3], s[4:5], v2, v1, v[22:23]
	v_lshlrev_b32_e32 v22, 7, v42
	v_mov_b32_e32 v23, v4
	v_lshl_add_u64 v[2:3], v[2:3], 0, v[22:23]
	v_mov_b32_e32 v1, v4
	v_lshl_add_u64 v[0:1], v[2:3], 0, v[0:1]
	v_cvt_pk_bf16_f32 v2, v6, v7
	v_cvt_pk_bf16_f32 v3, v8, v9
	s_nop 0
	v_readfirstlane_b32 s70, v0
	v_readfirstlane_b32 s71, v1
	ds_write_b64 v182, v[2:3]
	v_cvt_pk_bf16_f32 v2, v10, v11
	v_cvt_pk_bf16_f32 v3, v12, v13
	ds_write_b64 v182, v[2:3] offset:16
	v_cvt_pk_bf16_f32 v2, v14, v15
	v_cvt_pk_bf16_f32 v3, v16, v17
	ds_write_b64 v182, v[2:3] offset:32
	v_cvt_pk_bf16_f32 v2, v18, v19
	v_cvt_pk_bf16_f32 v3, v20, v21
	ds_write_b64 v182, v[2:3] offset:48
	ds_read_b128 v[186:189], v183
	ds_read_b128 v[190:193], v183 offset:1280
	s_waitcnt lgkmcnt(1)
	global_store_dwordx4 v185, v[186:189], s[70:71] offset:64
	s_waitcnt lgkmcnt(0)
	global_store_dwordx4 v185, v[190:193], s[70:71] offset:2112

.LBB0_972:
	s_or_b64 exec, exec, s[0:1]
	v_add_u32_e32 v154, v3, v139
	v_ashrrev_i32_e32 v155, 31, v154
	v_lshlrev_b64 v[2:3], v2, v[154:155]
	v_mov_b32_e32 v145, v4
	v_lshl_add_u64 v[146:147], s[26:27], 0, v[146:147]
	v_lshl_add_u64 v[2:3], v[2:3], 0, v[144:145]
	v_mad_u64_u32 v[144:145], s[0:1], v2, s50, v[146:147]
	v_mad_i32_i24 v145, v3, s50, v145
	v_ashrrev_i32_e32 v135, 31, v134
	v_lshl_add_u64 v[144:145], v[134:135], 1, v[144:145]
	v_lshlrev_b32_e32 v2, 1, v152
	v_mov_b32_e32 v3, v4
	v_pk_mul_f32 v[118:119], v[118:119], s[64:65] op_sel_hi:[1,0]
	v_pk_mul_f32 v[120:121], v[120:121], s[64:65] op_sel_hi:[1,0]
	v_lshl_add_u64 v[144:145], v[144:145], 0, v[2:3]
	v_cvt_pk_bf16_f32 v118, v118, v119
	v_cvt_pk_bf16_f32 v119, v120, v121
	s_nop 0
	v_readfirstlane_b32 s70, v144
	v_readfirstlane_b32 s71, v145
	ds_write_b64 v182, v[118:119]
	v_pk_mul_f32 v[118:119], v[122:123], s[64:65] op_sel_hi:[1,0]
	v_pk_mul_f32 v[120:121], v[124:125], s[64:65] op_sel_hi:[1,0]
	v_cvt_pk_bf16_f32 v118, v118, v119
	v_cvt_pk_bf16_f32 v119, v120, v121
	ds_write_b64 v182, v[118:119] offset:16
	v_pk_mul_f32 v[118:119], v[126:127], s[64:65] op_sel_hi:[1,0]
	v_pk_mul_f32 v[120:121], v[128:129], s[64:65] op_sel_hi:[1,0]
	v_cvt_pk_bf16_f32 v118, v118, v119
	v_cvt_pk_bf16_f32 v119, v120, v121
	ds_write_b64 v182, v[118:119] offset:32
	v_pk_mul_f32 v[118:119], v[130:131], s[64:65] op_sel_hi:[1,0]
	v_pk_mul_f32 v[120:121], v[132:133], s[64:65] op_sel_hi:[1,0]
	v_cvt_pk_bf16_f32 v118, v118, v119
	v_cvt_pk_bf16_f32 v119, v120, v121
	v_mov_b64_e32 v[122:123], 0xb152000
	v_mov_b64_e32 v[120:121], 8
	v_mov_b32_e32 v3, v148
	ds_write_b64 v182, v[118:119] offset:48
	ds_read_b128 v[186:189], v183
	ds_read_b128 v[190:193], v183 offset:1280
	s_waitcnt lgkmcnt(1)
	global_store_dwordx4 v184, v[186:189], s[70:71]
	s_waitcnt lgkmcnt(0)
	global_store_dwordx4 v184, v[190:193], s[70:71] offset:3072
	s_and_saveexec_b64 s[0:1], s[6:7]
	v_mov_b64_e32 v[122:123], 0xbd52000
	v_mov_b64_e32 v[120:121], 12
	v_mov_b32_e32 v3, v150
	v_mov_b32_e32 v136, v137
	s_or_b64 exec, exec, s[0:1]
	v_or_b32_e32 v1, 32, v151
	s_mov_b32 s0, 0x2aaaaaab
	v_mul_hi_i32 v118, v1, s0
	v_lshrrev_b32_e32 v119, 31, v118
	v_ashrrev_i32_e32 v118, 4, v118
	v_add_u32_e32 v121, v118, v119
	s_movk_i32 s0, 0x60
	v_mul_lo_u32 v118, v121, s0
	v_sub_u32_e32 v118, v1, v118
	v_cmp_eq_u32_e64 s[4:5], 64, v118
	s_and_b64 s[6:7], s[6:7], s[4:5]
	s_and_saveexec_b64 s[0:1], s[6:7]
	s_cbranch_execz .LBB0_976
	v_readlane_b32 s6, v253, 31
	v_lshlrev_b32_e32 v124, 7, v136
	v_mov_b32_e32 v125, v4
	v_readlane_b32 s7, v253, 32
	v_mov_b32_e32 v1, v4
	s_nop 0
	v_lshl_add_u64 v[126:127], s[6:7], 0, v[124:125]
	v_readlane_b32 s6, v254, 47
	v_readlane_b32 s7, v254, 48
	v_lshl_add_u64 v[132:133], v[126:127], 0, v[0:1]
	s_nop 0
	v_lshl_add_u64 v[124:125], s[6:7], 0, v[124:125]
	v_lshl_add_u64 v[144:145], v[124:125], 0, v[0:1]
	global_load_dwordx4 v[124:127], v[132:133], off
	global_load_dwordx4 v[128:131], v[144:145], off
	s_waitcnt vmcnt(0)
	v_pk_mul_f32 v[146:147], v[106:107], v[128:129]
	s_nop 0
	v_pk_fma_f32 v[146:147], v[102:103], v[124:125], v[146:147] neg_lo:[0,0,1] neg_hi:[0,0,1]
	v_pk_mul_f32 v[102:103], v[102:103], v[128:129]
	s_nop 0
	v_pk_fma_f32 v[106:107], v[106:107], v[124:125], v[102:103]
	v_pk_mul_f32 v[102:103], v[108:109], v[130:131]
	s_nop 0
	v_pk_fma_f32 v[128:129], v[104:105], v[126:127], v[102:103] neg_lo:[0,0,1] neg_hi:[0,0,1]
	v_pk_mul_f32 v[102:103], v[104:105], v[130:131]
	s_nop 0
	v_pk_fma_f32 v[108:109], v[108:109], v[126:127], v[102:103]
	global_load_dwordx4 v[102:105], v[132:133], off offset:64
	global_load_dwordx4 v[124:127], v[144:145], off offset:64
	s_waitcnt vmcnt(0)
	v_pk_mul_f32 v[130:131], v[114:115], v[124:125]
	s_nop 0
	v_pk_fma_f32 v[130:131], v[110:111], v[102:103], v[130:131] neg_lo:[0,0,1] neg_hi:[0,0,1]
	v_pk_mul_f32 v[110:111], v[110:111], v[124:125]
	s_nop 0
	v_pk_fma_f32 v[114:115], v[114:115], v[102:103], v[110:111]
	v_pk_mul_f32 v[102:103], v[116:117], v[126:127]
	v_mov_b32_e32 v110, v130
	v_pk_fma_f32 v[124:125], v[112:113], v[104:105], v[102:103] neg_lo:[0,0,1] neg_hi:[0,0,1]
	v_pk_mul_f32 v[102:103], v[112:113], v[126:127]
	v_mov_b32_e32 v111, v131
	v_pk_fma_f32 v[116:117], v[116:117], v[104:105], v[102:103]
	v_mov_b32_e32 v102, v146
	v_mov_b32_e32 v103, v147
	v_mov_b32_e32 v104, v128
	v_mov_b32_e32 v105, v129
	v_mov_b32_e32 v112, v124
	v_mov_b32_e32 v113, v125
.LBB0_976:
	s_or_b64 exec, exec, s[0:1]
	v_add_u32_e32 v124, v3, v121
	v_ashrrev_i32_e32 v125, 31, v124
	v_lshlrev_b64 v[124:125], v120, v[124:125]
	v_mov_b32_e32 v137, v4
	v_lshl_add_u64 v[122:123], s[26:27], 0, v[122:123]
	v_lshl_add_u64 v[124:125], v[124:125], 0, v[136:137]
	v_mad_u64_u32 v[122:123], s[0:1], v124, s50, v[122:123]
	v_mad_i32_i24 v123, v125, s50, v123
	v_ashrrev_i32_e32 v119, 31, v118
	v_lshl_add_u64 v[122:123], v[118:119], 1, v[122:123]
	v_mov_b32_e32 v3, v4
	v_pk_mul_f32 v[102:103], v[102:103], s[64:65] op_sel_hi:[1,0]
	v_pk_mul_f32 v[104:105], v[104:105], s[64:65] op_sel_hi:[1,0]
	v_lshl_add_u64 v[122:123], v[122:123], 0, v[2:3]
	v_cvt_pk_bf16_f32 v102, v102, v103
	v_cvt_pk_bf16_f32 v103, v104, v105
	s_nop 0
	v_readfirstlane_b32 s70, v122
	v_readfirstlane_b32 s71, v123
	ds_write_b64 v182, v[102:103]
	v_pk_mul_f32 v[102:103], v[106:107], s[64:65] op_sel_hi:[1,0]
	v_pk_mul_f32 v[104:105], v[108:109], s[64:65] op_sel_hi:[1,0]
	v_cvt_pk_bf16_f32 v102, v102, v103
	v_cvt_pk_bf16_f32 v103, v104, v105
	ds_write_b64 v182, v[102:103] offset:16
	v_pk_mul_f32 v[102:103], v[110:111], s[64:65] op_sel_hi:[1,0]
	v_pk_mul_f32 v[104:105], v[112:113], s[64:65] op_sel_hi:[1,0]
	v_cvt_pk_bf16_f32 v102, v102, v103
	v_cvt_pk_bf16_f32 v103, v104, v105
	ds_write_b64 v182, v[102:103] offset:32
	v_pk_mul_f32 v[102:103], v[114:115], s[64:65] op_sel_hi:[1,0]
	v_pk_mul_f32 v[104:105], v[116:117], s[64:65] op_sel_hi:[1,0]
	v_or_b32_e32 v1, 32, v149
	v_cvt_pk_bf16_f32 v102, v102, v103
	v_cvt_pk_bf16_f32 v103, v104, v105
	v_cmp_lt_i32_e64 s[6:7], s89, v1
	s_movk_i32 s0, 0xbf
	v_add_u32_e32 v1, 0xffffe020, v149
	ds_write_b64 v182, v[102:103] offset:48
	ds_read_b128 v[186:189], v183
	ds_read_b128 v[190:193], v183 offset:1280
	s_waitcnt lgkmcnt(1)
	global_store_dwordx4 v184, v[186:189], s[70:71]
	s_waitcnt lgkmcnt(0)
	global_store_dwordx4 v184, v[190:193], s[70:71] offset:3072
	v_bitop3_b32 v102, v149, s0, 32 bitop3:0xc8
	s_movk_i32 s0, 0xfbf
	v_lshrrev_b32_e32 v1, 9, v1
	v_bitop3_b32 v103, v149, s0, 32 bitop3:0xc8
	v_and_b32_e32 v110, 0x7ffff8, v1
	v_mov_b64_e32 v[108:109], 0xb152000
	v_mov_b64_e32 v[104:105], 8
	v_mov_b32_e32 v3, v148
	v_mov_b32_e32 v106, v102
	s_and_saveexec_b64 s[0:1], s[6:7]
	v_mov_b64_e32 v[108:109], 0xbd52000
	v_mov_b64_e32 v[104:105], 12
	v_mov_b32_e32 v3, v110
	v_mov_b32_e32 v106, v103
	s_or_b64 exec, exec, s[0:1]
	s_and_b64 s[14:15], s[6:7], vcc
	s_and_saveexec_b64 s[0:1], s[14:15]
	s_cbranch_execz .LBB0_980
	v_readlane_b32 s14, v253, 31
	v_lshlrev_b32_e32 v112, 7, v106
	v_mov_b32_e32 v113, v4
	v_readlane_b32 s15, v253, 32
	v_mov_b32_e32 v1, v4
	s_nop 0
	v_lshl_add_u64 v[114:115], s[14:15], 0, v[112:113]
	v_readlane_b32 s14, v254, 47
	v_readlane_b32 s15, v254, 48
	v_lshl_add_u64 v[116:117], v[114:115], 0, v[0:1]
	s_nop 0
	v_lshl_add_u64 v[112:113], s[14:15], 0, v[112:113]
	v_lshl_add_u64 v[126:127], v[112:113], 0, v[0:1]
	global_load_dwordx4 v[112:115], v[116:117], off
	global_load_dwordx4 v[122:125], v[126:127], off
	s_waitcnt vmcnt(0)
	v_pk_mul_f32 v[128:129], v[90:91], v[122:123]
	s_nop 0
	v_pk_fma_f32 v[128:129], v[86:87], v[112:113], v[128:129] neg_lo:[0,0,1] neg_hi:[0,0,1]
	v_pk_mul_f32 v[86:87], v[86:87], v[122:123]
	s_nop 0
	v_pk_fma_f32 v[90:91], v[90:91], v[112:113], v[86:87]
	v_pk_mul_f32 v[86:87], v[92:93], v[124:125]
	s_nop 0
	v_pk_fma_f32 v[122:123], v[88:89], v[114:115], v[86:87] neg_lo:[0,0,1] neg_hi:[0,0,1]
	v_pk_mul_f32 v[86:87], v[88:89], v[124:125]
	s_nop 0
	v_pk_fma_f32 v[92:93], v[92:93], v[114:115], v[86:87]
	global_load_dwordx4 v[86:89], v[116:117], off offset:64
	global_load_dwordx4 v[112:115], v[126:127], off offset:64
	s_waitcnt vmcnt(0)
	v_pk_mul_f32 v[116:117], v[98:99], v[112:113]
	s_nop 0
	v_pk_fma_f32 v[116:117], v[94:95], v[86:87], v[116:117] neg_lo:[0,0,1] neg_hi:[0,0,1]
	v_pk_mul_f32 v[94:95], v[94:95], v[112:113]
	s_nop 0
	v_pk_fma_f32 v[98:99], v[98:99], v[86:87], v[94:95]
	v_pk_mul_f32 v[86:87], v[100:101], v[114:115]
	v_mov_b32_e32 v94, v116
	v_pk_fma_f32 v[112:113], v[96:97], v[88:89], v[86:87] neg_lo:[0,0,1] neg_hi:[0,0,1]
	v_pk_mul_f32 v[86:87], v[96:97], v[114:115]
	v_mov_b32_e32 v95, v117
	v_pk_fma_f32 v[100:101], v[100:101], v[88:89], v[86:87]
	v_mov_b32_e32 v86, v128
	v_mov_b32_e32 v87, v129
	v_mov_b32_e32 v88, v122
	v_mov_b32_e32 v89, v123
	v_mov_b32_e32 v96, v112
	v_mov_b32_e32 v97, v113
.LBB0_980:
	s_or_b64 exec, exec, s[0:1]
	v_add_u32_e32 v112, v3, v139
	v_ashrrev_i32_e32 v113, 31, v112
	v_lshlrev_b64 v[104:105], v104, v[112:113]
	v_mov_b32_e32 v107, v4
	v_lshl_add_u64 v[108:109], s[26:27], 0, v[108:109]
	v_lshl_add_u64 v[104:105], v[104:105], 0, v[106:107]
	v_mad_u64_u32 v[106:107], s[0:1], v104, s50, v[108:109]
	v_mad_i32_i24 v107, v105, s50, v107
	v_lshl_add_u64 v[104:105], v[134:135], 1, v[106:107]
	v_mov_b32_e32 v3, v4
	v_pk_mul_f32 v[86:87], v[86:87], s[64:65] op_sel_hi:[1,0]
	v_pk_mul_f32 v[88:89], v[88:89], s[64:65] op_sel_hi:[1,0]
	v_lshl_add_u64 v[104:105], v[104:105], 0, v[2:3]
	v_cvt_pk_bf16_f32 v86, v86, v87
	v_cvt_pk_bf16_f32 v87, v88, v89
	s_nop 0
	v_readfirstlane_b32 s70, v104
	v_readfirstlane_b32 s71, v105
	ds_write_b64 v182, v[86:87]
	v_pk_mul_f32 v[86:87], v[90:91], s[64:65] op_sel_hi:[1,0]
	v_pk_mul_f32 v[88:89], v[92:93], s[64:65] op_sel_hi:[1,0]
	v_cvt_pk_bf16_f32 v86, v86, v87
	v_cvt_pk_bf16_f32 v87, v88, v89
	ds_write_b64 v182, v[86:87] offset:16
	v_pk_mul_f32 v[86:87], v[94:95], s[64:65] op_sel_hi:[1,0]
	v_pk_mul_f32 v[88:89], v[96:97], s[64:65] op_sel_hi:[1,0]
	v_cvt_pk_bf16_f32 v86, v86, v87
	v_cvt_pk_bf16_f32 v87, v88, v89
	ds_write_b64 v182, v[86:87] offset:32
	v_pk_mul_f32 v[86:87], v[98:99], s[64:65] op_sel_hi:[1,0]
	v_pk_mul_f32 v[88:89], v[100:101], s[64:65] op_sel_hi:[1,0]
	v_cvt_pk_bf16_f32 v86, v86, v87
	v_cvt_pk_bf16_f32 v87, v88, v89
	ds_write_b64 v182, v[86:87] offset:48
	ds_read_b128 v[186:189], v183
	ds_read_b128 v[190:193], v183 offset:1280
	s_waitcnt lgkmcnt(1)
	global_store_dwordx4 v184, v[186:189], s[70:71]
	s_waitcnt lgkmcnt(0)
	global_store_dwordx4 v184, v[190:193], s[70:71] offset:3072
	v_mov_b64_e32 v[88:89], 0xb152000
	v_mov_b64_e32 v[86:87], 8
	v_mov_b32_e32 v3, v148
	s_and_saveexec_b64 s[0:1], s[6:7]
	v_mov_b64_e32 v[88:89], 0xbd52000
	v_mov_b64_e32 v[86:87], 12
	v_mov_b32_e32 v3, v110
	v_mov_b32_e32 v102, v103
	s_or_b64 exec, exec, s[0:1]
	s_and_b64 s[6:7], s[6:7], s[4:5]
	s_and_saveexec_b64 s[0:1], s[6:7]
	s_cbranch_execz .LBB0_984
	v_readlane_b32 s6, v253, 31
	v_lshlrev_b32_e32 v90, 7, v102
	v_mov_b32_e32 v91, v4
	v_readlane_b32 s7, v253, 32
	v_mov_b32_e32 v1, v4
	s_nop 0
	v_lshl_add_u64 v[92:93], s[6:7], 0, v[90:91]
	v_readlane_b32 s6, v254, 47
	v_readlane_b32 s7, v254, 48
	v_lshl_add_u64 v[98:99], v[92:93], 0, v[0:1]
	s_nop 0
	v_lshl_add_u64 v[90:91], s[6:7], 0, v[90:91]
	v_lshl_add_u64 v[100:101], v[90:91], 0, v[0:1]
	global_load_dwordx4 v[90:93], v[98:99], off
	global_load_dwordx4 v[94:97], v[100:101], off
	s_waitcnt vmcnt(0)
	v_pk_mul_f32 v[104:105], v[74:75], v[94:95]
	s_nop 0
	v_pk_fma_f32 v[104:105], v[70:71], v[90:91], v[104:105] neg_lo:[0,0,1] neg_hi:[0,0,1]
	v_pk_mul_f32 v[70:71], v[70:71], v[94:95]
	s_nop 0
	v_pk_fma_f32 v[74:75], v[74:75], v[90:91], v[70:71]
	v_pk_mul_f32 v[70:71], v[76:77], v[96:97]
	s_nop 0
	v_pk_fma_f32 v[94:95], v[72:73], v[92:93], v[70:71] neg_lo:[0,0,1] neg_hi:[0,0,1]
	v_pk_mul_f32 v[70:71], v[72:73], v[96:97]
	s_nop 0
	v_pk_fma_f32 v[76:77], v[76:77], v[92:93], v[70:71]
	global_load_dwordx4 v[70:73], v[98:99], off offset:64
	global_load_dwordx4 v[90:93], v[100:101], off offset:64
	s_waitcnt vmcnt(0)
	v_pk_mul_f32 v[96:97], v[82:83], v[90:91]
	s_nop 0
	v_pk_fma_f32 v[96:97], v[78:79], v[70:71], v[96:97] neg_lo:[0,0,1] neg_hi:[0,0,1]
	v_pk_mul_f32 v[78:79], v[78:79], v[90:91]
	s_nop 0
	v_pk_fma_f32 v[82:83], v[82:83], v[70:71], v[78:79]
	v_pk_mul_f32 v[70:71], v[84:85], v[92:93]
	v_mov_b32_e32 v78, v96
	v_pk_fma_f32 v[90:91], v[80:81], v[72:73], v[70:71] neg_lo:[0,0,1] neg_hi:[0,0,1]
	v_pk_mul_f32 v[70:71], v[80:81], v[92:93]
	v_mov_b32_e32 v79, v97
	v_pk_fma_f32 v[84:85], v[84:85], v[72:73], v[70:71]
	v_mov_b32_e32 v70, v104
	v_mov_b32_e32 v71, v105
	v_mov_b32_e32 v72, v94
	v_mov_b32_e32 v73, v95
	v_mov_b32_e32 v80, v90
	v_mov_b32_e32 v81, v91
.LBB0_984:
	s_or_b64 exec, exec, s[0:1]
	v_add_u32_e32 v90, v3, v121
	v_ashrrev_i32_e32 v91, 31, v90
	v_lshlrev_b64 v[86:87], v86, v[90:91]
	v_mov_b32_e32 v103, v4
	v_lshl_add_u64 v[88:89], s[26:27], 0, v[88:89]
	v_lshl_add_u64 v[86:87], v[86:87], 0, v[102:103]
	v_mad_u64_u32 v[88:89], s[0:1], v86, s50, v[88:89]
	v_mad_i32_i24 v89, v87, s50, v89
	v_lshl_add_u64 v[86:87], v[118:119], 1, v[88:89]
	v_mov_b32_e32 v3, v4
	v_pk_mul_f32 v[70:71], v[70:71], s[64:65] op_sel_hi:[1,0]
	v_pk_mul_f32 v[72:73], v[72:73], s[64:65] op_sel_hi:[1,0]
	v_lshl_add_u64 v[86:87], v[86:87], 0, v[2:3]
	v_cvt_pk_bf16_f32 v70, v70, v71
	v_cvt_pk_bf16_f32 v71, v72, v73
	s_nop 0
	v_readfirstlane_b32 s70, v86
	v_readfirstlane_b32 s71, v87
	ds_write_b64 v182, v[70:71]
	v_pk_mul_f32 v[70:71], v[74:75], s[64:65] op_sel_hi:[1,0]
	v_pk_mul_f32 v[72:73], v[76:77], s[64:65] op_sel_hi:[1,0]
	v_cvt_pk_bf16_f32 v70, v70, v71
	v_cvt_pk_bf16_f32 v71, v72, v73
	ds_write_b64 v182, v[70:71] offset:16
	v_pk_mul_f32 v[70:71], v[78:79], s[64:65] op_sel_hi:[1,0]
	v_pk_mul_f32 v[72:73], v[80:81], s[64:65] op_sel_hi:[1,0]
	v_cvt_pk_bf16_f32 v70, v70, v71
	v_cvt_pk_bf16_f32 v71, v72, v73
	ds_write_b64 v182, v[70:71] offset:32
	v_pk_mul_f32 v[70:71], v[82:83], s[64:65] op_sel_hi:[1,0]
	v_pk_mul_f32 v[72:73], v[84:85], s[64:65] op_sel_hi:[1,0]
	v_or_b32_e32 v1, 64, v149
	v_cvt_pk_bf16_f32 v70, v70, v71
	v_cvt_pk_bf16_f32 v71, v72, v73
	v_cmp_lt_i32_e64 s[6:7], s89, v1
	s_movk_i32 s0, 0xdf
	v_add_u32_e32 v1, 0xffffe040, v149
	ds_write_b64 v182, v[70:71] offset:48
	ds_read_b128 v[186:189], v183
	ds_read_b128 v[190:193], v183 offset:1280
	s_waitcnt lgkmcnt(1)
	global_store_dwordx4 v184, v[186:189], s[70:71]
	s_waitcnt lgkmcnt(0)
	global_store_dwordx4 v184, v[190:193], s[70:71] offset:3072
	v_bitop3_b32 v70, v149, s0, 64 bitop3:0xc8
	s_movk_i32 s0, 0xfdf
	v_lshrrev_b32_e32 v1, 9, v1
	v_bitop3_b32 v71, v149, s0, 64 bitop3:0xc8
	v_and_b32_e32 v78, 0x7ffff8, v1
	v_mov_b64_e32 v[76:77], 0xb152000
	v_mov_b64_e32 v[72:73], 8
	v_mov_b32_e32 v3, v148
	v_mov_b32_e32 v74, v70
	s_and_saveexec_b64 s[0:1], s[6:7]
	v_mov_b64_e32 v[76:77], 0xbd52000
	v_mov_b64_e32 v[72:73], 12
	v_mov_b32_e32 v3, v78
	v_mov_b32_e32 v74, v71
	s_or_b64 exec, exec, s[0:1]
	s_and_b64 s[14:15], s[6:7], vcc
	s_and_saveexec_b64 s[0:1], s[14:15]
	s_cbranch_execz .LBB0_988
	v_readlane_b32 s14, v253, 31
	v_lshlrev_b32_e32 v80, 7, v74
	v_mov_b32_e32 v81, v4
	v_readlane_b32 s15, v253, 32
	v_mov_b32_e32 v1, v4
	s_nop 0
	v_lshl_add_u64 v[82:83], s[14:15], 0, v[80:81]
	v_readlane_b32 s14, v254, 47
	v_readlane_b32 s15, v254, 48
	v_lshl_add_u64 v[88:89], v[82:83], 0, v[0:1]
	s_nop 0
	v_lshl_add_u64 v[80:81], s[14:15], 0, v[80:81]
	v_lshl_add_u64 v[90:91], v[80:81], 0, v[0:1]
	global_load_dwordx4 v[80:83], v[88:89], off
	global_load_dwordx4 v[84:87], v[90:91], off
	s_waitcnt vmcnt(0)
	v_pk_mul_f32 v[92:93], v[58:59], v[84:85]
	s_nop 0
	v_pk_fma_f32 v[92:93], v[54:55], v[80:81], v[92:93] neg_lo:[0,0,1] neg_hi:[0,0,1]
	v_pk_mul_f32 v[54:55], v[54:55], v[84:85]
	s_nop 0
	v_pk_fma_f32 v[58:59], v[58:59], v[80:81], v[54:55]
	v_pk_mul_f32 v[54:55], v[60:61], v[86:87]
	s_nop 0
	v_pk_fma_f32 v[84:85], v[56:57], v[82:83], v[54:55] neg_lo:[0,0,1] neg_hi:[0,0,1]
	v_pk_mul_f32 v[54:55], v[56:57], v[86:87]
	s_nop 0
	v_pk_fma_f32 v[60:61], v[60:61], v[82:83], v[54:55]
	global_load_dwordx4 v[54:57], v[88:89], off offset:64
	global_load_dwordx4 v[80:83], v[90:91], off offset:64
	s_waitcnt vmcnt(0)
	v_pk_mul_f32 v[86:87], v[66:67], v[80:81]
	s_nop 0
	v_pk_fma_f32 v[86:87], v[62:63], v[54:55], v[86:87] neg_lo:[0,0,1] neg_hi:[0,0,1]
	v_pk_mul_f32 v[62:63], v[62:63], v[80:81]
	s_nop 0
	v_pk_fma_f32 v[66:67], v[66:67], v[54:55], v[62:63]
	v_pk_mul_f32 v[54:55], v[68:69], v[82:83]
	v_mov_b32_e32 v62, v86
	v_pk_fma_f32 v[80:81], v[64:65], v[56:57], v[54:55] neg_lo:[0,0,1] neg_hi:[0,0,1]
	v_pk_mul_f32 v[54:55], v[64:65], v[82:83]
	v_mov_b32_e32 v63, v87
	v_pk_fma_f32 v[68:69], v[68:69], v[56:57], v[54:55]
	v_mov_b32_e32 v54, v92
	v_mov_b32_e32 v55, v93
	v_mov_b32_e32 v56, v84
	v_mov_b32_e32 v57, v85
	v_mov_b32_e32 v64, v80
	v_mov_b32_e32 v65, v81
.LBB0_988:
	s_or_b64 exec, exec, s[0:1]
	v_add_u32_e32 v80, v3, v139
	v_ashrrev_i32_e32 v81, 31, v80
	v_lshlrev_b64 v[72:73], v72, v[80:81]
	v_mov_b32_e32 v75, v4
	v_lshl_add_u64 v[76:77], s[26:27], 0, v[76:77]
	v_lshl_add_u64 v[72:73], v[72:73], 0, v[74:75]
	v_mad_u64_u32 v[74:75], s[0:1], v72, s50, v[76:77]
	v_mad_i32_i24 v75, v73, s50, v75
	v_lshl_add_u64 v[72:73], v[134:135], 1, v[74:75]
	v_mov_b32_e32 v3, v4
	v_pk_mul_f32 v[54:55], v[54:55], s[64:65] op_sel_hi:[1,0]
	v_pk_mul_f32 v[56:57], v[56:57], s[64:65] op_sel_hi:[1,0]
	v_lshl_add_u64 v[72:73], v[72:73], 0, v[2:3]
	v_cvt_pk_bf16_f32 v54, v54, v55
	v_cvt_pk_bf16_f32 v55, v56, v57
	s_nop 0
	v_readfirstlane_b32 s70, v72
	v_readfirstlane_b32 s71, v73
	ds_write_b64 v182, v[54:55]
	v_pk_mul_f32 v[54:55], v[58:59], s[64:65] op_sel_hi:[1,0]
	v_pk_mul_f32 v[56:57], v[60:61], s[64:65] op_sel_hi:[1,0]
	v_cvt_pk_bf16_f32 v54, v54, v55
	v_cvt_pk_bf16_f32 v55, v56, v57
	ds_write_b64 v182, v[54:55] offset:16
	v_pk_mul_f32 v[54:55], v[62:63], s[64:65] op_sel_hi:[1,0]
	v_pk_mul_f32 v[56:57], v[64:65], s[64:65] op_sel_hi:[1,0]
	v_cvt_pk_bf16_f32 v54, v54, v55
	v_cvt_pk_bf16_f32 v55, v56, v57
	ds_write_b64 v182, v[54:55] offset:32
	v_pk_mul_f32 v[54:55], v[66:67], s[64:65] op_sel_hi:[1,0]
	v_pk_mul_f32 v[56:57], v[68:69], s[64:65] op_sel_hi:[1,0]
	v_cvt_pk_bf16_f32 v54, v54, v55
	v_cvt_pk_bf16_f32 v55, v56, v57
	ds_write_b64 v182, v[54:55] offset:48
	ds_read_b128 v[186:189], v183
	ds_read_b128 v[190:193], v183 offset:1280
	s_waitcnt lgkmcnt(1)
	global_store_dwordx4 v184, v[186:189], s[70:71]
	s_waitcnt lgkmcnt(0)
	global_store_dwordx4 v184, v[190:193], s[70:71] offset:3072
	v_mov_b64_e32 v[56:57], 0xb152000
	v_mov_b64_e32 v[54:55], 8
	v_mov_b32_e32 v3, v148
	s_and_saveexec_b64 s[0:1], s[6:7]
	v_mov_b64_e32 v[56:57], 0xbd52000
	v_mov_b64_e32 v[54:55], 12
	v_mov_b32_e32 v3, v78
	v_mov_b32_e32 v70, v71
	s_or_b64 exec, exec, s[0:1]
	s_and_b64 s[6:7], s[6:7], s[4:5]
	s_and_saveexec_b64 s[0:1], s[6:7]
	s_cbranch_execz .LBB0_992
	v_readlane_b32 s6, v253, 31
	v_lshlrev_b32_e32 v58, 7, v70
	v_mov_b32_e32 v59, v4
	v_readlane_b32 s7, v253, 32
	v_mov_b32_e32 v1, v4
	s_nop 0
	v_lshl_add_u64 v[60:61], s[6:7], 0, v[58:59]
	v_readlane_b32 s6, v254, 47
	v_readlane_b32 s7, v254, 48
	v_lshl_add_u64 v[66:67], v[60:61], 0, v[0:1]
	s_nop 0
	v_lshl_add_u64 v[58:59], s[6:7], 0, v[58:59]
	v_lshl_add_u64 v[68:69], v[58:59], 0, v[0:1]
	global_load_dwordx4 v[58:61], v[66:67], off
	global_load_dwordx4 v[62:65], v[68:69], off
	s_waitcnt vmcnt(0)
	v_pk_mul_f32 v[72:73], v[42:43], v[62:63]
	s_nop 0
	v_pk_fma_f32 v[72:73], v[38:39], v[58:59], v[72:73] neg_lo:[0,0,1] neg_hi:[0,0,1]
	v_pk_mul_f32 v[38:39], v[38:39], v[62:63]
	s_nop 0
	v_pk_fma_f32 v[42:43], v[42:43], v[58:59], v[38:39]
	v_pk_mul_f32 v[38:39], v[44:45], v[64:65]
	s_nop 0
	v_pk_fma_f32 v[62:63], v[40:41], v[60:61], v[38:39] neg_lo:[0,0,1] neg_hi:[0,0,1]
	v_pk_mul_f32 v[38:39], v[40:41], v[64:65]
	s_nop 0
	v_pk_fma_f32 v[44:45], v[44:45], v[60:61], v[38:39]
	global_load_dwordx4 v[38:41], v[66:67], off offset:64
	global_load_dwordx4 v[58:61], v[68:69], off offset:64
	s_waitcnt vmcnt(0)
	v_pk_mul_f32 v[64:65], v[50:51], v[58:59]
	s_nop 0
	v_pk_fma_f32 v[64:65], v[46:47], v[38:39], v[64:65] neg_lo:[0,0,1] neg_hi:[0,0,1]
	v_pk_mul_f32 v[46:47], v[46:47], v[58:59]
	s_nop 0
	v_pk_fma_f32 v[50:51], v[50:51], v[38:39], v[46:47]
	v_pk_mul_f32 v[38:39], v[52:53], v[60:61]
	v_mov_b32_e32 v46, v64
	v_pk_fma_f32 v[58:59], v[48:49], v[40:41], v[38:39] neg_lo:[0,0,1] neg_hi:[0,0,1]
	v_pk_mul_f32 v[38:39], v[48:49], v[60:61]
	v_mov_b32_e32 v47, v65
	v_pk_fma_f32 v[52:53], v[52:53], v[40:41], v[38:39]
	v_mov_b32_e32 v38, v72
	v_mov_b32_e32 v39, v73
	v_mov_b32_e32 v40, v62
	v_mov_b32_e32 v41, v63
	v_mov_b32_e32 v48, v58
	v_mov_b32_e32 v49, v59
.LBB0_992:
	s_or_b64 exec, exec, s[0:1]
	v_add_u32_e32 v58, v3, v121
	v_ashrrev_i32_e32 v59, 31, v58
	v_lshlrev_b64 v[54:55], v54, v[58:59]
	v_mov_b32_e32 v71, v4
	v_lshl_add_u64 v[56:57], s[26:27], 0, v[56:57]
	v_lshl_add_u64 v[54:55], v[54:55], 0, v[70:71]
	v_mad_u64_u32 v[56:57], s[0:1], v54, s50, v[56:57]
	v_mad_i32_i24 v57, v55, s50, v57
	v_lshl_add_u64 v[54:55], v[118:119], 1, v[56:57]
	v_mov_b32_e32 v3, v4
	v_pk_mul_f32 v[38:39], v[38:39], s[64:65] op_sel_hi:[1,0]
	v_pk_mul_f32 v[40:41], v[40:41], s[64:65] op_sel_hi:[1,0]
	v_lshl_add_u64 v[54:55], v[54:55], 0, v[2:3]
	v_cvt_pk_bf16_f32 v38, v38, v39
	v_cvt_pk_bf16_f32 v39, v40, v41
	s_nop 0
	v_readfirstlane_b32 s70, v54
	v_readfirstlane_b32 s71, v55
	ds_write_b64 v182, v[38:39]
	v_pk_mul_f32 v[38:39], v[42:43], s[64:65] op_sel_hi:[1,0]
	v_pk_mul_f32 v[40:41], v[44:45], s[64:65] op_sel_hi:[1,0]
	v_cvt_pk_bf16_f32 v38, v38, v39
	v_cvt_pk_bf16_f32 v39, v40, v41
	ds_write_b64 v182, v[38:39] offset:16
	v_pk_mul_f32 v[38:39], v[46:47], s[64:65] op_sel_hi:[1,0]
	v_pk_mul_f32 v[40:41], v[48:49], s[64:65] op_sel_hi:[1,0]
	v_cvt_pk_bf16_f32 v38, v38, v39
	v_cvt_pk_bf16_f32 v39, v40, v41
	ds_write_b64 v182, v[38:39] offset:32
	v_pk_mul_f32 v[38:39], v[50:51], s[64:65] op_sel_hi:[1,0]
	v_pk_mul_f32 v[40:41], v[52:53], s[64:65] op_sel_hi:[1,0]
	v_or_b32_e32 v1, 0x60, v149
	v_cvt_pk_bf16_f32 v38, v38, v39
	v_cvt_pk_bf16_f32 v39, v40, v41
	v_cmp_lt_i32_e64 s[6:7], s89, v1
	s_movk_i32 s0, 0xff
	v_add_u32_e32 v1, 0xffffe060, v149
	ds_write_b64 v182, v[38:39] offset:48
	ds_read_b128 v[186:189], v183
	ds_read_b128 v[190:193], v183 offset:1280
	s_waitcnt lgkmcnt(1)
	global_store_dwordx4 v184, v[186:189], s[70:71]
	s_waitcnt lgkmcnt(0)
	global_store_dwordx4 v184, v[190:193], s[70:71] offset:3072
	v_bitop3_b32 v38, v149, s0, v251 bitop3:0xc8
	s_movk_i32 s0, 0xfff
	v_lshrrev_b32_e32 v1, 9, v1
	v_bitop3_b32 v39, v149, s0, v251 bitop3:0xc8
	v_and_b32_e32 v46, 0x7ffff8, v1
	v_mov_b64_e32 v[44:45], 0xb152000
	v_mov_b64_e32 v[40:41], 8
	v_mov_b32_e32 v3, v148
	v_mov_b32_e32 v42, v38
	s_and_saveexec_b64 s[0:1], s[6:7]
	v_mov_b64_e32 v[44:45], 0xbd52000
	v_mov_b64_e32 v[40:41], 12
	v_mov_b32_e32 v3, v46
	v_mov_b32_e32 v42, v39
	s_or_b64 exec, exec, s[0:1]
	s_and_b64 s[14:15], s[6:7], vcc
	s_and_saveexec_b64 s[0:1], s[14:15]
	s_cbranch_execz .LBB0_996
	v_readlane_b32 s14, v253, 31
	v_lshlrev_b32_e32 v48, 7, v42
	v_mov_b32_e32 v49, v4
	v_readlane_b32 s15, v253, 32
	v_mov_b32_e32 v1, v4
	s_nop 0
	v_lshl_add_u64 v[50:51], s[14:15], 0, v[48:49]
	v_readlane_b32 s14, v254, 47
	v_readlane_b32 s15, v254, 48
	v_lshl_add_u64 v[56:57], v[50:51], 0, v[0:1]
	s_nop 0
	v_lshl_add_u64 v[48:49], s[14:15], 0, v[48:49]
	v_lshl_add_u64 v[58:59], v[48:49], 0, v[0:1]
	global_load_dwordx4 v[48:51], v[56:57], off
	global_load_dwordx4 v[52:55], v[58:59], off
	s_waitcnt vmcnt(0)
	v_pk_mul_f32 v[60:61], v[26:27], v[52:53]
	s_nop 0
	v_pk_fma_f32 v[60:61], v[22:23], v[48:49], v[60:61] neg_lo:[0,0,1] neg_hi:[0,0,1]
	v_pk_mul_f32 v[22:23], v[22:23], v[52:53]
	s_nop 0
	v_pk_fma_f32 v[26:27], v[26:27], v[48:49], v[22:23]
	v_pk_mul_f32 v[22:23], v[28:29], v[54:55]
	s_nop 0
	v_pk_fma_f32 v[52:53], v[24:25], v[50:51], v[22:23] neg_lo:[0,0,1] neg_hi:[0,0,1]
	v_pk_mul_f32 v[22:23], v[24:25], v[54:55]
	s_nop 0
	v_pk_fma_f32 v[28:29], v[28:29], v[50:51], v[22:23]
	global_load_dwordx4 v[22:25], v[56:57], off offset:64
	global_load_dwordx4 v[48:51], v[58:59], off offset:64
	s_waitcnt vmcnt(0)
	v_pk_mul_f32 v[54:55], v[34:35], v[48:49]
	s_nop 0
	v_pk_fma_f32 v[54:55], v[30:31], v[22:23], v[54:55] neg_lo:[0,0,1] neg_hi:[0,0,1]
	v_pk_mul_f32 v[30:31], v[30:31], v[48:49]
	s_nop 0
	v_pk_fma_f32 v[34:35], v[34:35], v[22:23], v[30:31]
	v_pk_mul_f32 v[22:23], v[36:37], v[50:51]
	v_mov_b32_e32 v30, v54
	v_pk_fma_f32 v[48:49], v[32:33], v[24:25], v[22:23] neg_lo:[0,0,1] neg_hi:[0,0,1]
	v_pk_mul_f32 v[22:23], v[32:33], v[50:51]
	v_mov_b32_e32 v31, v55
	v_pk_fma_f32 v[36:37], v[36:37], v[24:25], v[22:23]
	v_mov_b32_e32 v22, v60
	v_mov_b32_e32 v23, v61
	v_mov_b32_e32 v24, v52
	v_mov_b32_e32 v25, v53
	v_mov_b32_e32 v32, v48
	v_mov_b32_e32 v33, v49
.LBB0_996:
	s_or_b64 exec, exec, s[0:1]
	v_add_u32_e32 v48, v3, v139
	v_ashrrev_i32_e32 v49, 31, v48
	v_lshlrev_b64 v[40:41], v40, v[48:49]
	v_mov_b32_e32 v43, v4
	v_lshl_add_u64 v[44:45], s[26:27], 0, v[44:45]
	v_lshl_add_u64 v[40:41], v[40:41], 0, v[42:43]
	v_mad_u64_u32 v[42:43], s[0:1], v40, s50, v[44:45]
	v_mad_i32_i24 v43, v41, s50, v43
	v_lshl_add_u64 v[40:41], v[134:135], 1, v[42:43]
	v_mov_b32_e32 v3, v4
	v_pk_mul_f32 v[22:23], v[22:23], s[64:65] op_sel_hi:[1,0]
	v_pk_mul_f32 v[24:25], v[24:25], s[64:65] op_sel_hi:[1,0]
	v_lshl_add_u64 v[40:41], v[40:41], 0, v[2:3]
	v_cvt_pk_bf16_f32 v22, v22, v23
	v_cvt_pk_bf16_f32 v23, v24, v25
	s_nop 0
	v_readfirstlane_b32 s70, v40
	v_readfirstlane_b32 s71, v41
	ds_write_b64 v182, v[22:23]
	v_pk_mul_f32 v[22:23], v[26:27], s[64:65] op_sel_hi:[1,0]
	v_pk_mul_f32 v[24:25], v[28:29], s[64:65] op_sel_hi:[1,0]
	v_cvt_pk_bf16_f32 v22, v22, v23
	v_cvt_pk_bf16_f32 v23, v24, v25
	ds_write_b64 v182, v[22:23] offset:16
	v_pk_mul_f32 v[22:23], v[30:31], s[64:65] op_sel_hi:[1,0]
	v_pk_mul_f32 v[24:25], v[32:33], s[64:65] op_sel_hi:[1,0]
	v_cvt_pk_bf16_f32 v22, v22, v23
	v_cvt_pk_bf16_f32 v23, v24, v25
	ds_write_b64 v182, v[22:23] offset:32
	v_pk_mul_f32 v[22:23], v[34:35], s[64:65] op_sel_hi:[1,0]
	v_pk_mul_f32 v[24:25], v[36:37], s[64:65] op_sel_hi:[1,0]
	v_cvt_pk_bf16_f32 v22, v22, v23
	v_cvt_pk_bf16_f32 v23, v24, v25
	ds_write_b64 v182, v[22:23] offset:48
	ds_read_b128 v[186:189], v183
	ds_read_b128 v[190:193], v183 offset:1280
	s_waitcnt lgkmcnt(1)
	global_store_dwordx4 v184, v[186:189], s[70:71]
	s_waitcnt lgkmcnt(0)
	global_store_dwordx4 v184, v[190:193], s[70:71] offset:3072
	v_mov_b64_e32 v[24:25], 0xb152000
	v_mov_b64_e32 v[22:23], 8
	s_and_saveexec_b64 s[0:1], s[6:7]
	v_mov_b64_e32 v[24:25], 0xbd52000
	v_mov_b64_e32 v[22:23], 12
	v_mov_b32_e32 v148, v46
	v_mov_b32_e32 v38, v39
	s_or_b64 exec, exec, s[0:1]
	s_and_b64 s[4:5], s[6:7], s[4:5]
	s_and_saveexec_b64 s[0:1], s[4:5]
	s_cbranch_execz .LBB0_915
	v_readlane_b32 s4, v253, 31
	v_lshlrev_b32_e32 v26, 7, v38
	v_mov_b32_e32 v27, v4
	v_readlane_b32 s5, v253, 32
	v_mov_b32_e32 v1, v4
	s_nop 0
	v_lshl_add_u64 v[28:29], s[4:5], 0, v[26:27]
	v_readlane_b32 s4, v254, 47
	v_readlane_b32 s5, v254, 48
	v_lshl_add_u64 v[34:35], v[28:29], 0, v[0:1]
	s_nop 0
	v_lshl_add_u64 v[26:27], s[4:5], 0, v[26:27]
	v_lshl_add_u64 v[0:1], v[26:27], 0, v[0:1]
	global_load_dwordx4 v[26:29], v[34:35], off
	global_load_dwordx4 v[30:33], v[0:1], off
	s_waitcnt vmcnt(0)
	v_pk_mul_f32 v[36:37], v[10:11], v[30:31]
	s_nop 0
	v_pk_fma_f32 v[36:37], v[6:7], v[26:27], v[36:37] neg_lo:[0,0,1] neg_hi:[0,0,1]
	v_pk_mul_f32 v[6:7], v[6:7], v[30:31]
	s_nop 0
	v_pk_fma_f32 v[10:11], v[10:11], v[26:27], v[6:7]
	v_pk_mul_f32 v[6:7], v[12:13], v[32:33]
	s_nop 0
	v_pk_fma_f32 v[30:31], v[8:9], v[28:29], v[6:7] neg_lo:[0,0,1] neg_hi:[0,0,1]
	v_pk_mul_f32 v[6:7], v[8:9], v[32:33]
	s_nop 0
	v_pk_fma_f32 v[12:13], v[12:13], v[28:29], v[6:7]
	global_load_dwordx4 v[6:9], v[34:35], off offset:64
	global_load_dwordx4 v[26:29], v[0:1], off offset:64
	s_waitcnt vmcnt(0)
	v_pk_mul_f32 v[0:1], v[18:19], v[26:27]
	s_nop 0
	v_pk_fma_f32 v[0:1], v[14:15], v[6:7], v[0:1] neg_lo:[0,0,1] neg_hi:[0,0,1]
	v_pk_mul_f32 v[14:15], v[14:15], v[26:27]
	s_nop 0
	v_pk_fma_f32 v[18:19], v[18:19], v[6:7], v[14:15]
	v_pk_mul_f32 v[6:7], v[20:21], v[28:29]
	v_mov_b32_e32 v14, v0
	v_pk_fma_f32 v[26:27], v[16:17], v[8:9], v[6:7] neg_lo:[0,0,1] neg_hi:[0,0,1]
	v_pk_mul_f32 v[6:7], v[16:17], v[28:29]
	v_mov_b32_e32 v15, v1
	v_pk_fma_f32 v[20:21], v[20:21], v[8:9], v[6:7]
	v_mov_b32_e32 v6, v36
	v_mov_b32_e32 v7, v37
	v_mov_b32_e32 v8, v30
	v_mov_b32_e32 v9, v31
	v_mov_b32_e32 v16, v26
	v_mov_b32_e32 v17, v27
	s_branch .LBB0_915
